# three-level wave priority at unit boundaries: K-loop 1, older group's epilogue 0, younger group's epilogue 3
# baseline (speedup 1.0000x reference)
; #define G_STAGE(bufoff, gbase, o0, h64) do { \
;         __builtin_amdgcn_global_load_lds((const unsigned*)((const char*)(gbase) + (o0)), (LAS unsigned*)(lds + (bufoff) + ldsw), 16, 0, 0); \
;         __builtin_amdgcn_global_load_lds((const unsigned*)((const char*)(gbase) + (h64) + (o0)), (LAS unsigned*)(lds + (bufoff) + ldsw + 8192), 16, 0, 0); } while (0)
; #define G_LDA(dst, b, h) do { _Pragma("unroll") for (int m = 0; m < 4; ++m) _Pragma("unroll") for (int k = 0; k < 2; ++k) dst[m][k] = *(const LAS bf16x8*)(lds + G_SA(b, h) + aoff + m * 2048 + k * 1024); } while (0)
; #define G_LDB(dst, b, h) do { _Pragma("unroll") for (int n = 0; n < 2; ++n) _Pragma("unroll") for (int k = 0; k < 2; ++k) dst[n][k] = *(const LAS bf16x8*)(lds + G_SB(b, h) + boff + n * 2048 + k * 1024); } while (0)
; #define G_SCHED __builtin_amdgcn_sched_barrier(0)
;     ...
;     for (;;) {
;         const bool has_next = sched_next<PH, SUB>(E.ws, E.layer, ui + 1, nxt, E.x);
;         if (!has_next) nxt = cur;
;         const char* nA = nxt.A; const char* nB = nxt.B;
; #pragma unroll 1
;         for (int t = 0; t < nt; t += 2) {
;             const bool last = (t == nt - 2);
;             const char* a1 = cA + (size_t)(t + 1) * ckA;
;             const char* a2 = last ? nA : cA + (size_t)(t + 2) * ckA; const char* b2 = last ? nB : cB + (size_t)(t + 2) * kB;
;             const char* a3 = a2 + ckA; const char* b3 = b2 + kB;
;             G_LDB(B0, 0, 0); G_SCHED; G_LDA(At, 0, 0); G_STAGE(G_SA(1, 1), a1 + chA, cA0, qA);
.LBB0_211:
	s_add_u32 s2, s2, 0x40080
	s_addc_u32 s3, s3, 0
	s_add_u32 s7, s22, 0x100
	s_addc_u32 s22, s23, 0
	s_mov_b32 s23, -2
	s_mov_b64 s[52:53], 0x40000
	s_mov_b64 s[54:55], 0x60000
	s_mov_b64 s[58:59], 0x20080
	s_mov_b64 s[62:63], 0x40080
	s_mov_b64 s[64:65], 0x60080
	s_cmp_eq_u32 s101, 2
	s_cselect_b32 s101, 0, s101
	s_setprio 1
	v_add_u32_e32 v255, 0x10000, v167
	s_add_u32 s4, s2, 0xfffc0080
	s_addc_u32 s5, s3, -1
	s_add_i32 s41, 0, 0x10000
	ds_read_b128 v[136:139], v255 offset:0
	ds_read_b128 v[144:147], v255 offset:1024
	ds_read_b128 v[148:151], v255 offset:2048
	ds_read_b128 v[152:155], v255 offset:3072
	s_cmp_eq_u32 s23, 12
	s_cselect_b32 s43, s19, s5
	s_cselect_b32 s42, s18, s4
	s_cselect_b32 s51, s21, s22
	s_cselect_b32 s50, s20, s7
	s_add_i32 m0, s27, 0xc000
	ds_read_b128 v[156:159], v172
	ds_read_b128 v[160:163], v172 offset:1024
	ds_read_b128 v[174:177], v172 offset:2048
	ds_read_b128 v[178:181], v172 offset:3072
	ds_read_b128 v[182:185], v172 offset:4096
	ds_read_b128 v[196:199], v172 offset:5120
	ds_read_b128 v[200:203], v172 offset:6144
	ds_read_b128 v[204:207], v172 offset:7168
	global_load_lds_dwordx4 v142, s[2:3]
	s_add_i32 m0, s27, 0xe000
	s_nop 0
	s_add_u32 vcc_lo, s2, s0
	s_addc_u32 vcc_hi, s3, s1
	global_load_lds_dwordx4 v142, vcc
	s_waitcnt lgkmcnt(8)
	s_cmp_eq_u32 s101, 1
	s_cbranch_scc1 .Ldb_WIN_skp
	s_barrier

;     ...
;         E.template run<cs.kind>(acc, cur, tid);
;         if (!has_next) break;
.Ldb_WIN_xl:
	v_readfirstlane_b32 s101, v186
	s_cmpk_gt_u32 s101, 0xff
	s_cbranch_scc1 .Ldb_WIN_young
	s_barrier
	s_mov_b32 s101, 1
	s_setprio 0
	s_branch .Ldb_WIN_exit

; #define G_STAGE(bufoff, gbase, o0, h64) do { \
;         __builtin_amdgcn_global_load_lds((const unsigned*)((const char*)(gbase) + (o0)), (LAS unsigned*)(lds + (bufoff) + ldsw), 16, 0, 0); \
;         __builtin_amdgcn_global_load_lds((const unsigned*)((const char*)(gbase) + (h64) + (o0)), (LAS unsigned*)(lds + (bufoff) + ldsw + 8192), 16, 0, 0); } while (0)
; #define G_LDA(dst, b, h) do { _Pragma("unroll") for (int m = 0; m < 4; ++m) _Pragma("unroll") for (int k = 0; k < 2; ++k) dst[m][k] = *(const LAS bf16x8*)(lds + G_SA(b, h) + aoff + m * 2048 + k * 1024); } while (0)
; #define G_LDB(dst, b, h) do { _Pragma("unroll") for (int n = 0; n < 2; ++n) _Pragma("unroll") for (int k = 0; k < 2; ++k) dst[n][k] = *(const LAS bf16x8*)(lds + G_SB(b, h) + boff + n * 2048 + k * 1024); } while (0)
; #define G_SCHED __builtin_amdgcn_sched_barrier(0)
;     ...
;     for (;;) {
;         const bool has_next = sched_next<PH, SUB>(E.ws, E.layer, ui + 1, nxt, E.x);
;         if (!has_next) nxt = cur;
;         const char* nA = nxt.A; const char* nB = nxt.B;
; #pragma unroll 1
;         for (int t = 0; t < nt; t += 2) {
;             const bool last = (t == nt - 2);
;             const char* a1 = cA + (size_t)(t + 1) * ckA;
;             const char* a2 = last ? nA : cA + (size_t)(t + 2) * ckA; const char* b2 = last ? nB : cB + (size_t)(t + 2) * kB;
;             const char* a3 = a2 + ckA; const char* b3 = b2 + kB;
;             G_LDB(B0, 0, 0); G_SCHED; G_LDA(At, 0, 0); G_STAGE(G_SA(1, 1), a1 + chA, cA0, qA);
.LBB0_449:
	s_add_u32 s6, s22, 0x20080
	s_addc_u32 s7, s23, 0
	s_add_u32 s19, s20, 0x100
	s_addc_u32 s20, s21, 0
	s_mov_b32 s21, -2
	s_mov_b64 s[50:51], 0x20080
	s_mov_b64 s[52:53], 0x10000
	s_mov_b64 s[54:55], 0x30000
	s_mov_b64 s[58:59], 0x10080
	s_mov_b64 s[62:63], 0x30080
	s_cmp_eq_u32 s101, 2
	s_cselect_b32 s101, 0, s101
	s_setprio 1
	v_add_u32_e32 v255, 0x10000, v145
	s_add_u32 s4, s6, 0xfffe0080
	s_addc_u32 s5, s7, -1
	s_add_i32 s41, 0, 0x10000
	ds_read_b128 v[140:143], v255 offset:0
	ds_read_b128 v[148:151], v255 offset:1024
	ds_read_b128 v[152:155], v255 offset:2048
	ds_read_b128 v[156:159], v255 offset:3072
	s_cmp_eq_u32 s21, 4
	s_cselect_b32 s23, s11, s5
	s_cselect_b32 s22, s10, s4
	s_cselect_b32 s43, s17, s20
	s_cselect_b32 s42, s16, s19
	s_add_i32 m0, s27, 0xc000
	ds_read_b128 v[160:163], v146
	ds_read_b128 v[164:167], v146 offset:1024
	ds_read_b128 v[172:175], v146 offset:2048
	ds_read_b128 v[176:179], v146 offset:3072
	ds_read_b128 v[180:183], v146 offset:4096
	ds_read_b128 v[196:199], v146 offset:5120
	ds_read_b128 v[200:203], v146 offset:6144
	ds_read_b128 v[204:207], v146 offset:7168
	global_load_lds_dwordx4 v138, s[6:7]
	s_add_i32 m0, s27, 0xe000
	s_nop 0
	s_add_u32 vcc_lo, s6, s52
	s_addc_u32 vcc_hi, s7, s53
	global_load_lds_dwordx4 v138, vcc
	s_waitcnt lgkmcnt(8)
	s_cmp_eq_u32 s101, 1
	s_cbranch_scc1 .Ldb_SSM1_skp
	s_barrier

;     ...
;     for (;;) {
;         const bool has_next = sched_next<PH, SUB>(E.ws, E.layer, ui + 1, nxt, E.x);
;         if (!has_next) nxt = cur;
;         const char* nA = nxt.A; const char* nB = nxt.B;
;     ...
;         if (!(cs.kind == K_MG_B && cur.aux < 2))
; #pragma unroll
;         for (int a = 0; a < 2; ++a)
; #pragma unroll
;             for (int b = 0; b < 2; ++b)
; #pragma unroll
;                 for (int m = 0; m < 4; ++m)
; #pragma unroll
;                     for (int n = 0; n < 2; ++n) acc[a][b][m][n] = (f32x4){0.f, 0.f, 0.f, 0.f};
.LBB0_741:
	v_mov_b64_e32 v[8:9], 0
	s_mov_b64 s[30:31], 0
	s_mov_b64 s[24:25], -1
	s_mov_b64 s[26:27], 0
	v_mov_b64_e32 v[10:11], 0
	v_mov_b64_e32 v[12:13], 0
	v_mov_b64_e32 v[14:15], 0
	v_mov_b64_e32 v[24:25], 0
	v_mov_b64_e32 v[26:27], 0
	v_mov_b64_e32 v[28:29], 0
	v_mov_b64_e32 v[30:31], 0
	v_mov_b64_e32 v[40:41], 0
	v_mov_b64_e32 v[42:43], 0
	v_mov_b64_e32 v[44:45], 0
	v_mov_b64_e32 v[46:47], 0
	v_mov_b64_e32 v[64:65], 0
	v_mov_b64_e32 v[66:67], 0
	v_mov_b64_e32 v[68:69], 0
	v_mov_b64_e32 v[70:71], 0
	v_mov_b64_e32 v[16:17], 0
	v_mov_b64_e32 v[18:19], 0
	v_mov_b64_e32 v[20:21], 0
	v_mov_b64_e32 v[22:23], 0
	v_mov_b64_e32 v[32:33], 0
	v_mov_b64_e32 v[34:35], 0
	v_mov_b64_e32 v[36:37], 0
	v_mov_b64_e32 v[38:39], 0
	v_mov_b64_e32 v[48:49], 0
	v_mov_b64_e32 v[50:51], 0
	v_mov_b64_e32 v[52:53], 0
	v_mov_b64_e32 v[54:55], 0
	v_mov_b64_e32 v[72:73], 0
	v_mov_b64_e32 v[74:75], 0
	v_mov_b64_e32 v[76:77], 0
	v_mov_b64_e32 v[78:79], 0
	v_mov_b64_e32 v[80:81], 0
	v_mov_b64_e32 v[82:83], 0
	v_mov_b64_e32 v[84:85], 0
	v_mov_b64_e32 v[86:87], 0
	v_mov_b64_e32 v[96:97], 0
	v_mov_b64_e32 v[98:99], 0
	v_mov_b64_e32 v[100:101], 0
	v_mov_b64_e32 v[102:103], 0
	v_mov_b64_e32 v[112:113], 0
	v_mov_b64_e32 v[114:115], 0
	v_mov_b64_e32 v[116:117], 0
	v_mov_b64_e32 v[118:119], 0
	v_mov_b64_e32 v[128:129], 0
	v_mov_b64_e32 v[130:131], 0
	v_mov_b64_e32 v[132:133], 0
	v_mov_b64_e32 v[134:135], 0
	v_mov_b64_e32 v[88:89], 0
	v_mov_b64_e32 v[90:91], 0
	v_mov_b64_e32 v[92:93], 0
	v_mov_b64_e32 v[94:95], 0
	v_mov_b64_e32 v[104:105], 0
	v_mov_b64_e32 v[106:107], 0
	v_mov_b64_e32 v[108:109], 0
	v_mov_b64_e32 v[110:111], 0
	v_mov_b64_e32 v[120:121], 0
	v_mov_b64_e32 v[122:123], 0
	v_mov_b64_e32 v[124:125], 0
	v_mov_b64_e32 v[126:127], 0
	v_mov_b64_e32 v[136:137], 0
	v_mov_b64_e32 v[138:139], 0
	v_mov_b64_e32 v[140:141], 0
	v_mov_b64_e32 v[142:143], 0
	s_mov_b64 s[82:83], 0x10000
	s_mov_b64 s[84:85], 0x10080
	s_mov_b64 s[86:87], 0x200000
	s_mov_b64 s[88:89], 0x100000
	s_mov_b64 s[92:93], 0x8000
	s_mov_b64 s[94:95], 0x18000
	s_mov_b64 s[96:97], 0x300000
	s_mov_b64 s[70:71], 0x8080
	s_mov_b64 s[68:69], 0x100080
	s_mov_b64 s[28:29], 0x18080
	s_cmp_eq_u32 s101, 2
	s_cselect_b32 s101, 0, s101
	s_setprio 1
	v_add_u32_e32 v255, 0x10000, v183

; #define G_STAGE(bufoff, gbase, o0, h64) do { \
;         __builtin_amdgcn_global_load_lds((const unsigned*)((const char*)(gbase) + (o0)), (LAS unsigned*)(lds + (bufoff) + ldsw), 16, 0, 0); \
;         __builtin_amdgcn_global_load_lds((const unsigned*)((const char*)(gbase) + (h64) + (o0)), (LAS unsigned*)(lds + (bufoff) + ldsw + 8192), 16, 0, 0); } while (0)
; #define G_LDA(dst, b, h) do { _Pragma("unroll") for (int m = 0; m < 4; ++m) _Pragma("unroll") for (int k = 0; k < 2; ++k) dst[m][k] = *(const LAS bf16x8*)(lds + G_SA(b, h) + aoff + m * 2048 + k * 1024); } while (0)
; #define G_LDB(dst, b, h) do { _Pragma("unroll") for (int n = 0; n < 2; ++n) _Pragma("unroll") for (int k = 0; k < 2; ++k) dst[n][k] = *(const LAS bf16x8*)(lds + G_SB(b, h) + boff + n * 2048 + k * 1024); } while (0)
; #define G_WAIT_V(n) asm volatile("s_waitcnt vmcnt(" #n ")" ::: "memory")
; #define G_WAIT_L(n) asm volatile("s_waitcnt lgkmcnt(" #n ")" ::: "memory")
; #define G_BAR __builtin_amdgcn_s_barrier()
; #define G_SCHED __builtin_amdgcn_sched_barrier(0)
;     ...
;             G_LDB(B0, 0, 0); G_SCHED; G_LDA(At, 0, 0); G_STAGE(G_SA(1, 1), a1 + chA, cA0, qA);
;             G_WAIT_L(8); G_BAR; G_WAIT_L(0); G_MMA(0, 0, At, B0); G_BAR; G_SCHED;
;             G_LDB(B1, 0, 1); G_STAGE(G_SB(0, 0), b2, cB0, qB);
;             G_BAR; G_WAIT_L(0); G_MMA(0, 1, At, B1); G_BAR;
;             G_LDA(At, 0, 1); G_STAGE(G_SA(0, 0), a2, cA0, qA);
;             G_BAR; G_WAIT_L(0); G_MMA(1, 0, At, B0); G_BAR; G_SCHED;
;             G_STAGE(G_SB(0, 1), b2 + chB, cB0, qB);
;             G_WAIT_V(6); G_BAR; G_MMA(1, 1, At, B1); G_BAR;
;             G_LDB(B0, 1, 0); G_SCHED; G_LDA(At, 1, 0); G_STAGE(G_SA(0, 1), a2 + chA, cA0, qA);
;             G_WAIT_L(8); G_BAR; G_WAIT_L(0); G_MMA(0, 0, At, B0); G_BAR; G_SCHED;
.Ldb_SSM2_sk:
	s_mov_b32 s101, 0
	s_waitcnt lgkmcnt(0)
	v_mfma_f32_16x16x32_bf16 v[140:143], v[56:59], v[152:155], v[140:143]
	v_mfma_f32_16x16x32_bf16 v[136:139], v[144:147], v[152:155], v[136:139]
	v_mfma_f32_16x16x32_bf16 v[124:127], v[56:59], v[162:165], v[124:127]
	v_mfma_f32_16x16x32_bf16 v[120:123], v[144:147], v[162:165], v[120:123]
	v_mfma_f32_16x16x32_bf16 v[108:111], v[56:59], v[176:179], v[108:111]
	v_mfma_f32_16x16x32_bf16 v[104:107], v[144:147], v[176:179], v[104:107]
	v_mfma_f32_16x16x32_bf16 v[92:95], v[56:59], v[200:203], v[92:95]
	v_mfma_f32_16x16x32_bf16 v[88:91], v[144:147], v[200:203], v[88:91]
	v_mfma_f32_16x16x32_bf16 v[140:143], v[60:63], v[156:159], v[140:143]
	v_mfma_f32_16x16x32_bf16 v[136:139], v[148:151], v[156:159], v[136:139]
	v_mfma_f32_16x16x32_bf16 v[124:127], v[60:63], v[172:175], v[124:127]
	v_mfma_f32_16x16x32_bf16 v[120:123], v[148:151], v[172:175], v[120:123]
	v_mfma_f32_16x16x32_bf16 v[108:111], v[60:63], v[196:199], v[108:111]
	v_mfma_f32_16x16x32_bf16 v[104:107], v[148:151], v[196:199], v[104:107]
	v_mfma_f32_16x16x32_bf16 v[92:95], v[60:63], v[204:207], v[92:95]
	v_mfma_f32_16x16x32_bf16 v[88:91], v[148:151], v[204:207], v[88:91]
	s_barrier
	s_mov_b32 m0, s49
	ds_read_b128 v[208:211], v255 offset:16384
	ds_read_b128 v[212:215], v255 offset:17408
	ds_read_b128 v[216:219], v255 offset:18432
	ds_read_b128 v[220:223], v255 offset:19456
	global_load_lds_dwordx4 v2, s[26:27]
	s_mov_b32 m0, s66
	s_nop 0
	s_add_u32 vcc_lo, s26, s92
	s_addc_u32 vcc_hi, s27, s93
	global_load_lds_dwordx4 v2, vcc
	s_barrier
	s_waitcnt lgkmcnt(0)
	v_mfma_f32_16x16x32_bf16 v[132:135], v[208:211], v[152:155], v[132:135]
	v_mfma_f32_16x16x32_bf16 v[128:131], v[216:219], v[152:155], v[128:131]
	v_mfma_f32_16x16x32_bf16 v[116:119], v[208:211], v[162:165], v[116:119]
	v_mfma_f32_16x16x32_bf16 v[112:115], v[216:219], v[162:165], v[112:115]
	v_mfma_f32_16x16x32_bf16 v[100:103], v[208:211], v[176:179], v[100:103]
	v_mfma_f32_16x16x32_bf16 v[96:99], v[216:219], v[176:179], v[96:99]
	v_mfma_f32_16x16x32_bf16 v[84:87], v[208:211], v[200:203], v[84:87]
	v_mfma_f32_16x16x32_bf16 v[80:83], v[216:219], v[200:203], v[80:83]
	v_mfma_f32_16x16x32_bf16 v[132:135], v[212:215], v[156:159], v[132:135]
	v_mfma_f32_16x16x32_bf16 v[128:131], v[220:223], v[156:159], v[128:131]
	v_mfma_f32_16x16x32_bf16 v[116:119], v[212:215], v[172:175], v[116:119]
	v_mfma_f32_16x16x32_bf16 v[112:115], v[220:223], v[172:175], v[112:115]
	v_mfma_f32_16x16x32_bf16 v[100:103], v[212:215], v[196:199], v[100:103]
	v_mfma_f32_16x16x32_bf16 v[96:99], v[220:223], v[196:199], v[96:99]
	v_mfma_f32_16x16x32_bf16 v[84:87], v[212:215], v[204:207], v[84:87]
	v_mfma_f32_16x16x32_bf16 v[80:83], v[220:223], v[204:207], v[80:83]
	s_barrier
	s_mov_b32 m0, s43
	ds_read_b128 v[152:155], v184 offset:16384
	ds_read_b128 v[156:159], v184 offset:17408
	ds_read_b128 v[162:165], v184 offset:18432
	ds_read_b128 v[172:175], v184 offset:19456
	ds_read_b128 v[176:179], v184 offset:20480
	ds_read_b128 v[196:199], v184 offset:21504
	ds_read_b128 v[200:203], v184 offset:22528
	ds_read_b128 v[204:207], v184 offset:23552
	global_load_lds_dwordx4 v160, s[34:35]
	s_mov_b32 m0, s50
	s_nop 0
	s_add_u32 vcc_lo, s34, s88
	s_addc_u32 vcc_hi, s35, s89
	global_load_lds_dwordx4 v160, vcc
	s_barrier
	s_waitcnt lgkmcnt(0)
	v_mfma_f32_16x16x32_bf16 v[76:79], v[56:59], v[152:155], v[76:79]
	v_mfma_f32_16x16x32_bf16 v[72:75], v[144:147], v[152:155], v[72:75]
	v_mfma_f32_16x16x32_bf16 v[52:55], v[56:59], v[162:165], v[52:55]
	v_mfma_f32_16x16x32_bf16 v[48:51], v[144:147], v[162:165], v[48:51]
	v_mfma_f32_16x16x32_bf16 v[36:39], v[56:59], v[176:179], v[36:39]
	v_mfma_f32_16x16x32_bf16 v[32:35], v[144:147], v[176:179], v[32:35]
	v_mfma_f32_16x16x32_bf16 v[20:23], v[56:59], v[200:203], v[20:23]
	v_mfma_f32_16x16x32_bf16 v[16:19], v[144:147], v[200:203], v[16:19]
	v_mfma_f32_16x16x32_bf16 v[76:79], v[60:63], v[156:159], v[76:79]
	v_mfma_f32_16x16x32_bf16 v[72:75], v[148:151], v[156:159], v[72:75]
	v_mfma_f32_16x16x32_bf16 v[52:55], v[60:63], v[172:175], v[52:55]
	v_mfma_f32_16x16x32_bf16 v[48:51], v[148:151], v[172:175], v[48:51]
	v_mfma_f32_16x16x32_bf16 v[36:39], v[60:63], v[196:199], v[36:39]
	v_mfma_f32_16x16x32_bf16 v[32:35], v[148:151], v[196:199], v[32:35]
	v_mfma_f32_16x16x32_bf16 v[20:23], v[60:63], v[204:207], v[20:23]
	v_mfma_f32_16x16x32_bf16 v[16:19], v[148:151], v[204:207], v[16:19]
	s_barrier
	s_mov_b32 m0, s63
	s_add_u32 vcc_lo, s26, s82
	s_addc_u32 vcc_hi, s27, s83
	global_load_lds_dwordx4 v2, vcc
	s_mov_b32 m0, s62
	s_nop 0
	s_add_u32 vcc_lo, s26, s94
	s_addc_u32 vcc_hi, s27, s95
	global_load_lds_dwordx4 v2, vcc
	s_waitcnt vmcnt(6)
	s_barrier
	v_mfma_f32_16x16x32_bf16 v[44:47], v[208:211], v[162:165], v[44:47]
	v_mfma_f32_16x16x32_bf16 v[40:43], v[216:219], v[162:165], v[40:43]
	v_mfma_f32_16x16x32_bf16 v[28:31], v[208:211], v[176:179], v[28:31]
	v_mfma_f32_16x16x32_bf16 v[24:27], v[216:219], v[176:179], v[24:27]
	v_mfma_f32_16x16x32_bf16 v[12:15], v[208:211], v[200:203], v[12:15]
	v_mfma_f32_16x16x32_bf16 v[8:11], v[216:219], v[200:203], v[8:11]
	v_mfma_f32_16x16x32_bf16 v[56:59], v[208:211], v[152:155], v[68:71]
	v_mfma_f32_16x16x32_bf16 v[60:63], v[216:219], v[152:155], v[64:67]
	v_mfma_f32_16x16x32_bf16 v[44:47], v[212:215], v[172:175], v[44:47]
	v_mfma_f32_16x16x32_bf16 v[40:43], v[220:223], v[172:175], v[40:43]
	v_mfma_f32_16x16x32_bf16 v[28:31], v[212:215], v[196:199], v[28:31]
	v_mfma_f32_16x16x32_bf16 v[24:27], v[220:223], v[196:199], v[24:27]
	v_mfma_f32_16x16x32_bf16 v[12:15], v[212:215], v[204:207], v[12:15]
	v_mfma_f32_16x16x32_bf16 v[8:11], v[220:223], v[204:207], v[8:11]
	v_mfma_f32_16x16x32_bf16 v[56:59], v[212:215], v[156:159], v[56:59]
	v_mfma_f32_16x16x32_bf16 v[60:63], v[220:223], v[156:159], v[60:63]
	s_barrier
; #define G_STAGE(bufoff, gbase, o0, h64) do { \
;         __builtin_amdgcn_global_load_lds((const unsigned*)((const char*)(gbase) + (o0)), (LAS unsigned*)(lds + (bufoff) + ldsw), 16, 0, 0); \
;         __builtin_amdgcn_global_load_lds((const unsigned*)((const char*)(gbase) + (h64) + (o0)), (LAS unsigned*)(lds + (bufoff) + ldsw + 8192), 16, 0, 0); } while (0)
; #define G_LDA(dst, b, h) do { _Pragma("unroll") for (int m = 0; m < 4; ++m) _Pragma("unroll") for (int k = 0; k < 2; ++k) dst[m][k] = *(const LAS bf16x8*)(lds + G_SA(b, h) + aoff + m * 2048 + k * 1024); } while (0)
; #define G_LDB(dst, b, h) do { _Pragma("unroll") for (int n = 0; n < 2; ++n) _Pragma("unroll") for (int k = 0; k < 2; ++k) dst[n][k] = *(const LAS bf16x8*)(lds + G_SB(b, h) + boff + n * 2048 + k * 1024); } while (0)
; #define G_WAIT_V(n) asm volatile("s_waitcnt vmcnt(" #n ")" ::: "memory")
; #define G_WAIT_L(n) asm volatile("s_waitcnt lgkmcnt(" #n ")" ::: "memory")
; #define G_BAR __builtin_amdgcn_s_barrier()
; #define G_SCHED __builtin_amdgcn_sched_barrier(0)
;     ...
;             G_WAIT_L(8); G_BAR; G_WAIT_L(0); G_MMA(0, 0, At, B0); G_BAR; G_SCHED;
;             G_LDB(B1, 1, 1); G_STAGE(G_SB(1, 0), b3, cB0, qB);
;             G_BAR; G_WAIT_L(0); G_MMA(0, 1, At, B1); G_BAR;
;             G_LDA(At, 1, 1); G_STAGE(G_SA(1, 0), a3, cA0, qA);
;             G_BAR; G_WAIT_L(0); G_MMA(1, 0, At, B0); G_BAR; G_SCHED;
;             G_STAGE(G_SB(1, 1), b3 + chB, cB0, qB);
;             G_WAIT_V(6); G_BAR; G_MMA(1, 1, At, B1); G_BAR;
;         }
;         E.template run<cs.kind>(acc, cur, tid);
;         if (!has_next) break;
	ds_read_b128 v[64:67], v255 offset:32768
	ds_read_b128 v[68:71], v255 offset:33792
	ds_read_b128 v[144:147], v255 offset:34816
	ds_read_b128 v[148:151], v255 offset:35840
	s_mov_b32 m0, s51
	ds_read_b128 v[152:155], v184 offset:32768
	ds_read_b128 v[156:159], v184 offset:33792
	ds_read_b128 v[162:165], v184 offset:34816
	ds_read_b128 v[172:175], v184 offset:35840
	ds_read_b128 v[176:179], v184 offset:36864
	ds_read_b128 v[196:199], v184 offset:37888
	ds_read_b128 v[200:203], v184 offset:38912
	ds_read_b128 v[204:207], v184 offset:39936
	s_add_u32 vcc_lo, s34, s86
	s_addc_u32 vcc_hi, s35, s87
	global_load_lds_dwordx4 v160, vcc
	s_mov_b32 m0, s52
	s_nop 0
	s_add_u32 vcc_lo, s34, s96
	s_addc_u32 vcc_hi, s35, s97
	global_load_lds_dwordx4 v160, vcc
	s_waitcnt lgkmcnt(8)
	s_barrier
	s_waitcnt lgkmcnt(0)
	v_mfma_f32_16x16x32_bf16 v[140:143], v[64:67], v[152:155], v[140:143]
	v_mfma_f32_16x16x32_bf16 v[136:139], v[144:147], v[152:155], v[136:139]
	v_mfma_f32_16x16x32_bf16 v[124:127], v[64:67], v[162:165], v[124:127]
	v_mfma_f32_16x16x32_bf16 v[120:123], v[144:147], v[162:165], v[120:123]
	v_mfma_f32_16x16x32_bf16 v[108:111], v[64:67], v[176:179], v[108:111]
	v_mfma_f32_16x16x32_bf16 v[104:107], v[144:147], v[176:179], v[104:107]
	v_mfma_f32_16x16x32_bf16 v[92:95], v[64:67], v[200:203], v[92:95]
	v_mfma_f32_16x16x32_bf16 v[88:91], v[144:147], v[200:203], v[88:91]
	v_mfma_f32_16x16x32_bf16 v[140:143], v[68:71], v[156:159], v[140:143]
	v_mfma_f32_16x16x32_bf16 v[136:139], v[148:151], v[156:159], v[136:139]
	v_mfma_f32_16x16x32_bf16 v[124:127], v[68:71], v[172:175], v[124:127]
	v_mfma_f32_16x16x32_bf16 v[120:123], v[148:151], v[172:175], v[120:123]
	v_mfma_f32_16x16x32_bf16 v[108:111], v[68:71], v[196:199], v[108:111]
	v_mfma_f32_16x16x32_bf16 v[104:107], v[148:151], v[196:199], v[104:107]
	v_mfma_f32_16x16x32_bf16 v[92:95], v[68:71], v[204:207], v[92:95]
	v_mfma_f32_16x16x32_bf16 v[88:91], v[148:151], v[204:207], v[88:91]
	s_barrier
	s_mov_b32 m0, s30
	ds_read_b128 v[208:211], v255 offset:49152
	ds_read_b128 v[212:215], v255 offset:50176
	ds_read_b128 v[216:219], v255 offset:51200
	ds_read_b128 v[220:223], v255 offset:52224
	s_add_u32 vcc_lo, s26, s46
	s_addc_u32 vcc_hi, s27, s47
	global_load_lds_dwordx4 v2, vcc
	s_mov_b32 m0, s67
	s_nop 0
	s_add_u32 vcc_lo, s26, s70
	s_addc_u32 vcc_hi, s27, s71
	global_load_lds_dwordx4 v2, vcc
	s_barrier
	s_waitcnt lgkmcnt(0)
	v_mfma_f32_16x16x32_bf16 v[132:135], v[208:211], v[152:155], v[132:135]
	v_mfma_f32_16x16x32_bf16 v[128:131], v[216:219], v[152:155], v[128:131]
	v_mfma_f32_16x16x32_bf16 v[116:119], v[208:211], v[162:165], v[116:119]
	v_mfma_f32_16x16x32_bf16 v[112:115], v[216:219], v[162:165], v[112:115]
	v_mfma_f32_16x16x32_bf16 v[100:103], v[208:211], v[176:179], v[100:103]
	v_mfma_f32_16x16x32_bf16 v[96:99], v[216:219], v[176:179], v[96:99]
	v_mfma_f32_16x16x32_bf16 v[84:87], v[208:211], v[200:203], v[84:87]
	v_mfma_f32_16x16x32_bf16 v[80:83], v[216:219], v[200:203], v[80:83]
	v_mfma_f32_16x16x32_bf16 v[132:135], v[212:215], v[156:159], v[132:135]
	v_mfma_f32_16x16x32_bf16 v[128:131], v[220:223], v[156:159], v[128:131]
	v_mfma_f32_16x16x32_bf16 v[116:119], v[212:215], v[172:175], v[116:119]
	v_mfma_f32_16x16x32_bf16 v[112:115], v[220:223], v[172:175], v[112:115]
	v_mfma_f32_16x16x32_bf16 v[100:103], v[212:215], v[196:199], v[100:103]
	v_mfma_f32_16x16x32_bf16 v[96:99], v[220:223], v[196:199], v[96:99]
	v_mfma_f32_16x16x32_bf16 v[84:87], v[212:215], v[204:207], v[84:87]
	v_mfma_f32_16x16x32_bf16 v[80:83], v[220:223], v[204:207], v[80:83]
	s_barrier
	s_mov_b32 m0, s53
	ds_read_b128 v[152:155], v184 offset:49152
	ds_read_b128 v[156:159], v184 offset:50176
	ds_read_b128 v[162:165], v184 offset:51200
	ds_read_b128 v[172:175], v184 offset:52224
	ds_read_b128 v[176:179], v184 offset:53248
	ds_read_b128 v[196:199], v184 offset:54272
	ds_read_b128 v[200:203], v184 offset:55296
	ds_read_b128 v[204:207], v184 offset:56320
	s_add_u32 vcc_lo, s34, s46
	s_addc_u32 vcc_hi, s35, s47
	global_load_lds_dwordx4 v160, vcc
	s_mov_b32 m0, s54
	s_nop 0
	s_add_u32 vcc_lo, s34, s68
	s_addc_u32 vcc_hi, s35, s69
	global_load_lds_dwordx4 v160, vcc
	s_barrier
	s_waitcnt lgkmcnt(0)
	v_mfma_f32_16x16x32_bf16 v[76:79], v[64:67], v[152:155], v[76:79]
	v_mfma_f32_16x16x32_bf16 v[72:75], v[144:147], v[152:155], v[72:75]
	v_mfma_f32_16x16x32_bf16 v[52:55], v[64:67], v[162:165], v[52:55]
	v_mfma_f32_16x16x32_bf16 v[48:51], v[144:147], v[162:165], v[48:51]
	v_mfma_f32_16x16x32_bf16 v[36:39], v[64:67], v[176:179], v[36:39]
	v_mfma_f32_16x16x32_bf16 v[32:35], v[144:147], v[176:179], v[32:35]
	v_mfma_f32_16x16x32_bf16 v[20:23], v[64:67], v[200:203], v[20:23]
	v_mfma_f32_16x16x32_bf16 v[16:19], v[144:147], v[200:203], v[16:19]
	v_mfma_f32_16x16x32_bf16 v[76:79], v[68:71], v[156:159], v[76:79]
	v_mfma_f32_16x16x32_bf16 v[72:75], v[148:151], v[156:159], v[72:75]
	v_mfma_f32_16x16x32_bf16 v[52:55], v[68:71], v[172:175], v[52:55]
	v_mfma_f32_16x16x32_bf16 v[48:51], v[148:151], v[172:175], v[48:51]
	v_mfma_f32_16x16x32_bf16 v[36:39], v[68:71], v[196:199], v[36:39]
	v_mfma_f32_16x16x32_bf16 v[32:35], v[148:151], v[196:199], v[32:35]
	v_mfma_f32_16x16x32_bf16 v[20:23], v[68:71], v[204:207], v[20:23]
	v_mfma_f32_16x16x32_bf16 v[16:19], v[148:151], v[204:207], v[16:19]
	s_barrier
	s_mov_b32 m0, s65
	s_add_u32 vcc_lo, s26, s84
	s_addc_u32 vcc_hi, s27, s85
	global_load_lds_dwordx4 v2, vcc
	s_mov_b32 m0, s64
	s_nop 0
	s_add_u32 vcc_lo, s26, s28
	s_addc_u32 vcc_hi, s27, s29
	global_load_lds_dwordx4 v2, vcc
	s_waitcnt vmcnt(6)
	s_barrier
	v_mfma_f32_16x16x32_bf16 v[56:59], v[208:211], v[152:155], v[56:59]
	v_mfma_f32_16x16x32_bf16 v[68:71], v[212:215], v[156:159], v[56:59]
	v_mfma_f32_16x16x32_bf16 v[56:59], v[216:219], v[152:155], v[60:63]
	v_mfma_f32_16x16x32_bf16 v[44:47], v[208:211], v[162:165], v[44:47]
	v_mfma_f32_16x16x32_bf16 v[40:43], v[216:219], v[162:165], v[40:43]
	v_mfma_f32_16x16x32_bf16 v[28:31], v[208:211], v[176:179], v[28:31]
	v_mfma_f32_16x16x32_bf16 v[24:27], v[216:219], v[176:179], v[24:27]
	v_mfma_f32_16x16x32_bf16 v[12:15], v[208:211], v[200:203], v[12:15]
	v_mfma_f32_16x16x32_bf16 v[8:11], v[216:219], v[200:203], v[8:11]
	v_mfma_f32_16x16x32_bf16 v[64:67], v[220:223], v[156:159], v[56:59]
	v_mfma_f32_16x16x32_bf16 v[44:47], v[212:215], v[172:175], v[44:47]
	v_mfma_f32_16x16x32_bf16 v[40:43], v[220:223], v[172:175], v[40:43]
	v_mfma_f32_16x16x32_bf16 v[28:31], v[212:215], v[196:199], v[28:31]
	v_mfma_f32_16x16x32_bf16 v[24:27], v[220:223], v[196:199], v[24:27]
	v_mfma_f32_16x16x32_bf16 v[12:15], v[212:215], v[204:207], v[12:15]
	v_mfma_f32_16x16x32_bf16 v[8:11], v[220:223], v[204:207], v[8:11]
	s_andn2_b64 vcc, exec, s[24:25]
	s_mov_b64 s[26:27], -1
	s_mov_b64 s[24:25], 0
	s_mov_b64 s[30:31], 0x100
	s_cbranch_vccz .Ldb_SSM2_cont
	v_readfirstlane_b32 s101, v186
	s_cmpk_gt_u32 s101, 0xff
	s_cbranch_scc1 .Ldb_SSM2_young
	s_barrier
	s_mov_b32 s101, 1
	s_setprio 0
	s_branch .Ldb_SSM2_exit

; #define G_STAGE(bufoff, gbase, o0, h64) do { \
;         __builtin_amdgcn_global_load_lds((const unsigned*)((const char*)(gbase) + (o0)), (LAS unsigned*)(lds + (bufoff) + ldsw), 16, 0, 0); \
;         __builtin_amdgcn_global_load_lds((const unsigned*)((const char*)(gbase) + (h64) + (o0)), (LAS unsigned*)(lds + (bufoff) + ldsw + 8192), 16, 0, 0); } while (0)
; #define G_LDA(dst, b, h) do { _Pragma("unroll") for (int m = 0; m < 4; ++m) _Pragma("unroll") for (int k = 0; k < 2; ++k) dst[m][k] = *(const LAS bf16x8*)(lds + G_SA(b, h) + aoff + m * 2048 + k * 1024); } while (0)
; #define G_LDB(dst, b, h) do { _Pragma("unroll") for (int n = 0; n < 2; ++n) _Pragma("unroll") for (int k = 0; k < 2; ++k) dst[n][k] = *(const LAS bf16x8*)(lds + G_SB(b, h) + boff + n * 2048 + k * 1024); } while (0)
; #define G_SCHED __builtin_amdgcn_sched_barrier(0)
;     ...
;     for (;;) {
;         const bool has_next = sched_next<PH, SUB>(E.ws, E.layer, ui + 1, nxt, E.x);
;         if (!has_next) nxt = cur;
;         const char* nA = nxt.A; const char* nB = nxt.B;
; #pragma unroll 1
;         for (int t = 0; t < nt; t += 2) {
;             const bool last = (t == nt - 2);
;             const char* a1 = cA + (size_t)(t + 1) * ckA;
;             const char* a2 = last ? nA : cA + (size_t)(t + 2) * ckA; const char* b2 = last ? nB : cB + (size_t)(t + 2) * kB;
;             const char* a3 = a2 + ckA; const char* b3 = b2 + kB;
;             G_LDB(B0, 0, 0); G_SCHED; G_LDA(At, 0, 0); G_STAGE(G_SA(1, 1), a1 + chA, cA0, qA);
.LBB0_803:
	s_add_u32 s13, s18, 0x100
	s_addc_u32 s18, s19, 0
	s_add_u32 s2, s2, 0x800000
	s_addc_u32 s3, s3, 0
	s_mov_b32 s19, -2
	s_mov_b64 s[42:43], 0x20080
	s_mov_b64 s[50:51], 0x10000
	s_mov_b64 s[52:53], 0x30000
	s_mov_b64 s[54:55], 0x10080
	s_mov_b64 s[58:59], 0x30080
	s_mov_b64 s[62:63], 0x400000
	s_cmp_eq_u32 s101, 2
	s_cselect_b32 s101, 0, s101
	s_setprio 1
	v_add_u32_e32 v255, 0x10000, v196
	s_add_i32 s40, 0, 0x10000
	ds_read_b128 v[112:115], v255 offset:0
	ds_read_b128 v[124:127], v255 offset:1024
	ds_read_b128 v[136:139], v255 offset:2048
	ds_read_b128 v[148:151], v255 offset:3072
	s_cmp_eq_u32 s19, 4
	s_cselect_b32 s5, s15, s3
	s_cselect_b32 s4, s14, s2
	s_cselect_b32 s37, s17, s18
	s_cselect_b32 s36, s16, s13
	s_mov_b32 s38, 0xffc01000
	s_mov_b32 s39, -1
	s_add_u32 vcc_lo, s2, s38
	s_addc_u32 vcc_hi, s3, s39
	s_mov_b32 s38, 0xffc01800
	s_add_i32 m0, s24, 0xc000
	s_mov_b32 s39, -1
	ds_read_b128 v[152:155], v197
	ds_read_b128 v[156:159], v197 offset:1024
	ds_read_b128 v[160:163], v197 offset:2048
	ds_read_b128 v[172:175], v197 offset:3072
	ds_read_b128 v[176:179], v197 offset:4096
	ds_read_b128 v[180:183], v197 offset:5120
	ds_read_b128 v[198:201], v197 offset:6144
	ds_read_b128 v[202:205], v197 offset:7168
	global_load_lds_dwordx4 v166, vcc
	s_add_i32 m0, s24, 0xe000
	s_nop 0
	s_add_u32 vcc_lo, s2, s38
	s_addc_u32 vcc_hi, s3, s39
	global_load_lds_dwordx4 v166, vcc
	s_waitcnt lgkmcnt(8)
	s_cmp_eq_u32 s101, 1
	s_cbranch_scc1 .Ldb_GLU_skp
	s_barrier

; #define G_STAGE(bufoff, gbase, o0, h64) do { \
;         __builtin_amdgcn_global_load_lds((const unsigned*)((const char*)(gbase) + (o0)), (LAS unsigned*)(lds + (bufoff) + ldsw), 16, 0, 0); \
;         __builtin_amdgcn_global_load_lds((const unsigned*)((const char*)(gbase) + (h64) + (o0)), (LAS unsigned*)(lds + (bufoff) + ldsw + 8192), 16, 0, 0); } while (0)
; #define G_LDA(dst, b, h) do { _Pragma("unroll") for (int m = 0; m < 4; ++m) _Pragma("unroll") for (int k = 0; k < 2; ++k) dst[m][k] = *(const LAS bf16x8*)(lds + G_SA(b, h) + aoff + m * 2048 + k * 1024); } while (0)
; #define G_LDB(dst, b, h) do { _Pragma("unroll") for (int n = 0; n < 2; ++n) _Pragma("unroll") for (int k = 0; k < 2; ++k) dst[n][k] = *(const LAS bf16x8*)(lds + G_SB(b, h) + boff + n * 2048 + k * 1024); } while (0)
; #define G_SCHED __builtin_amdgcn_sched_barrier(0)
;     ...
;     for (;;) {
;         const bool has_next = sched_next<PH, SUB>(E.ws, E.layer, ui + 1, nxt, E.x);
;         if (!has_next) nxt = cur;
;         const char* nA = nxt.A; const char* nB = nxt.B;
; #pragma unroll 1
;         for (int t = 0; t < nt; t += 2) {
;             const bool last = (t == nt - 2);
;             const char* a1 = cA + (size_t)(t + 1) * ckA;
;             const char* a2 = last ? nA : cA + (size_t)(t + 2) * ckA; const char* b2 = last ? nB : cB + (size_t)(t + 2) * kB;
;             const char* a3 = a2 + ckA; const char* b3 = b2 + kB;
;             G_LDB(B0, 0, 0); G_SCHED; G_LDA(At, 0, 0); G_STAGE(G_SA(1, 1), a1 + chA, cA0, qA);
.LBB0_871:
	s_add_u32 s2, s2, 0xb0080
	s_addc_u32 s3, s3, 0
	s_add_u32 s37, s12, 0x100
	s_addc_u32 s38, s13, 0
	s_mov_b32 s39, -2
	s_mov_b64 s[42:43], 0x20080
	s_mov_b64 s[50:51], 0x10000
	s_mov_b64 s[52:53], 0x30000
	s_mov_b64 s[54:55], 0x10080
	s_mov_b64 s[58:59], 0x30080
	s_cmp_eq_u32 s101, 2
	s_cselect_b32 s101, 0, s101
	s_setprio 1
	v_add_u32_e32 v239, 0x10000, v159
	s_add_u32 s4, s2, 0xfff50080
	s_addc_u32 s5, s3, -1
	s_add_i32 s40, 0, 0x10000
	ds_read_b128 v[144:147], v239 offset:0
	ds_read_b128 v[148:151], v239 offset:1024
	ds_read_b128 v[136:139], v239 offset:2048
	ds_read_b128 v[140:143], v239 offset:3072
	s_cmp_eq_u32 s39, 4
	s_cselect_b32 s13, s9, s5
	s_cselect_b32 s12, s8, s4
	s_cselect_b32 s15, s11, s38
	s_cselect_b32 s14, s10, s37
	s_add_i32 m0, s22, 0xc000
	ds_read_b128 v[160:163], v236
	ds_read_b128 v[164:167], v236 offset:1024
	ds_read_b128 v[176:179], v236 offset:2048
	ds_read_b128 v[180:183], v236 offset:3072
	ds_read_b128 v[196:199], v236 offset:4096
	ds_read_b128 v[200:203], v236 offset:5120
	ds_read_b128 v[204:207], v236 offset:6144
	ds_read_b128 v[208:211], v236 offset:7168
	global_load_lds_dwordx4 v152, s[2:3]
	s_add_i32 m0, s22, 0xe000
	s_nop 0
	s_add_u32 vcc_lo, s2, s86
	s_addc_u32 vcc_hi, s3, s87
	global_load_lds_dwordx4 v152, vcc
	s_waitcnt lgkmcnt(8)
	s_cmp_eq_u32 s101, 1
	s_cbranch_scc1 .Ldb_MG0_skp
	s_barrier

;     ...
;     for (;;) {
;         const bool has_next = sched_next<PH, SUB>(E.ws, E.layer, ui + 1, nxt, E.x);
;         if (!has_next) nxt = cur;
;         const char* nA = nxt.A; const char* nB = nxt.B;
.LBB0_889:
	s_add_u32 s6, s6, 0xb0080
	s_addc_u32 s7, s7, 0
	s_add_u32 s8, s18, 0x100
	s_addc_u32 s9, s19, 0
	s_mov_b32 s18, -2
	s_mov_b64 s[50:51], 0x20080
	s_mov_b64 s[52:53], 0x30000
	s_mov_b64 s[54:55], 0x10080
	s_mov_b64 s[58:59], 0x30080
	s_cmp_eq_u32 s101, 2
	s_cselect_b32 s101, 0, s101
	s_setprio 1
	v_add_u32_e32 v239, 0x10000, v175

; #define G_STAGE(bufoff, gbase, o0, h64) do { \
;         __builtin_amdgcn_global_load_lds((const unsigned*)((const char*)(gbase) + (o0)), (LAS unsigned*)(lds + (bufoff) + ldsw), 16, 0, 0); \
;         __builtin_amdgcn_global_load_lds((const unsigned*)((const char*)(gbase) + (h64) + (o0)), (LAS unsigned*)(lds + (bufoff) + ldsw + 8192), 16, 0, 0); } while (0)
; #define G_LDA(dst, b, h) do { _Pragma("unroll") for (int m = 0; m < 4; ++m) _Pragma("unroll") for (int k = 0; k < 2; ++k) dst[m][k] = *(const LAS bf16x8*)(lds + G_SA(b, h) + aoff + m * 2048 + k * 1024); } while (0)
; #define G_LDB(dst, b, h) do { _Pragma("unroll") for (int n = 0; n < 2; ++n) _Pragma("unroll") for (int k = 0; k < 2; ++k) dst[n][k] = *(const LAS bf16x8*)(lds + G_SB(b, h) + boff + n * 2048 + k * 1024); } while (0)
; #define G_WAIT_V(n) asm volatile("s_waitcnt vmcnt(" #n ")" ::: "memory")
; #define G_WAIT_L(n) asm volatile("s_waitcnt lgkmcnt(" #n ")" ::: "memory")
; #define G_BAR __builtin_amdgcn_s_barrier()
; #define G_SCHED __builtin_amdgcn_sched_barrier(0)
;     ...
;             G_LDB(B0, 0, 0); G_SCHED; G_LDA(At, 0, 0); G_STAGE(G_SA(1, 1), a1 + chA, cA0, qA);
;             G_WAIT_L(8); G_BAR; G_WAIT_L(0); G_MMA(0, 0, At, B0); G_BAR; G_SCHED;
;             G_LDB(B1, 0, 1); G_STAGE(G_SB(0, 0), b2, cB0, qB);
;             G_BAR; G_WAIT_L(0); G_MMA(0, 1, At, B1); G_BAR;
;             G_LDA(At, 0, 1); G_STAGE(G_SA(0, 0), a2, cA0, qA);
;             G_BAR; G_WAIT_L(0); G_MMA(1, 0, At, B0); G_BAR; G_SCHED;
;             G_STAGE(G_SB(0, 1), b2 + chB, cB0, qB);
;             G_WAIT_V(6); G_BAR; G_MMA(1, 1, At, B1); G_BAR;
;             G_LDB(B0, 1, 0); G_SCHED; G_LDA(At, 1, 0); G_STAGE(G_SA(0, 1), a2 + chA, cA0, qA);
;             G_WAIT_L(8); G_BAR; G_WAIT_L(0); G_MMA(0, 0, At, B0); G_BAR; G_SCHED;
.Ldb_MG1_sk:
	s_mov_b32 s101, 0
	s_waitcnt lgkmcnt(0)
	v_mfma_f32_16x16x32_bf16 v[104:107], v[136:139], v[158:161], v[104:107]
	v_mfma_f32_16x16x32_bf16 v[108:111], v[144:147], v[158:161], v[108:111]
	v_mfma_f32_16x16x32_bf16 v[132:135], v[136:139], v[178:181], v[132:135]
	v_mfma_f32_16x16x32_bf16 v[128:131], v[144:147], v[178:181], v[128:131]
	v_mfma_f32_16x16x32_bf16 v[124:127], v[136:139], v[196:199], v[124:127]
	v_mfma_f32_16x16x32_bf16 v[120:123], v[144:147], v[196:199], v[120:123]
	v_mfma_f32_16x16x32_bf16 v[116:119], v[136:139], v[204:207], v[116:119]
	v_mfma_f32_16x16x32_bf16 v[112:115], v[144:147], v[204:207], v[112:115]
	v_mfma_f32_16x16x32_bf16 v[104:107], v[140:143], v[162:165], v[104:107]
	v_mfma_f32_16x16x32_bf16 v[108:111], v[148:151], v[162:165], v[108:111]
	v_mfma_f32_16x16x32_bf16 v[132:135], v[140:143], v[182:185], v[132:135]
	v_mfma_f32_16x16x32_bf16 v[128:131], v[148:151], v[182:185], v[128:131]
	v_mfma_f32_16x16x32_bf16 v[124:127], v[140:143], v[200:203], v[124:127]
	v_mfma_f32_16x16x32_bf16 v[120:123], v[148:151], v[200:203], v[120:123]
	v_mfma_f32_16x16x32_bf16 v[116:119], v[140:143], v[208:211], v[116:119]
	v_mfma_f32_16x16x32_bf16 v[112:115], v[148:151], v[208:211], v[112:115]
	s_barrier
	s_add_i32 s43, 0, 0x14000
	s_add_i32 s19, s19, s21
	v_lshl_add_u64 v[2:3], s[44:45], 0, v[154:155]
	s_mov_b64 vcc, s[44:45]
	s_mov_b64 s[44:45], 0x10000
	s_mov_b32 m0, s19
	ds_read_b128 v[212:215], v239 offset:16384
	ds_read_b128 v[216:219], v239 offset:17408
	ds_read_b128 v[220:223], v239 offset:18432
	ds_read_b128 v[224:227], v239 offset:19456
	global_load_lds_dwordx4 v154, vcc
	v_lshl_add_u64 v[166:167], v[2:3], 0, s[44:45]
	s_add_i32 m0, s19, 0x2000
	s_nop 0
	global_load_lds_dwordx4 v[166:167], off
	s_barrier
	s_waitcnt lgkmcnt(0)
	v_mfma_f32_16x16x32_bf16 v[100:103], v[212:215], v[158:161], v[100:103]
	v_mfma_f32_16x16x32_bf16 v[96:99], v[220:223], v[158:161], v[96:99]
	v_mfma_f32_16x16x32_bf16 v[92:95], v[212:215], v[178:181], v[92:95]
	v_mfma_f32_16x16x32_bf16 v[88:91], v[220:223], v[178:181], v[88:91]
	v_mfma_f32_16x16x32_bf16 v[84:87], v[212:215], v[196:199], v[84:87]
	v_mfma_f32_16x16x32_bf16 v[80:83], v[220:223], v[196:199], v[80:83]
	v_mfma_f32_16x16x32_bf16 v[76:79], v[212:215], v[204:207], v[76:79]
	v_mfma_f32_16x16x32_bf16 v[72:75], v[220:223], v[204:207], v[72:75]
	v_mfma_f32_16x16x32_bf16 v[100:103], v[216:219], v[162:165], v[100:103]
	v_mfma_f32_16x16x32_bf16 v[96:99], v[224:227], v[162:165], v[96:99]
	v_mfma_f32_16x16x32_bf16 v[92:95], v[216:219], v[182:185], v[92:95]
	v_mfma_f32_16x16x32_bf16 v[88:91], v[224:227], v[182:185], v[88:91]
	v_mfma_f32_16x16x32_bf16 v[84:87], v[216:219], v[200:203], v[84:87]
	v_mfma_f32_16x16x32_bf16 v[80:83], v[224:227], v[200:203], v[80:83]
	v_mfma_f32_16x16x32_bf16 v[76:79], v[216:219], v[208:211], v[76:79]
	v_mfma_f32_16x16x32_bf16 v[72:75], v[224:227], v[208:211], v[72:75]
	s_barrier
	s_mov_b32 m0, s22
	v_lshl_add_u64 v[166:167], s[4:5], 0, v[152:153]
	ds_read_b128 v[158:161], v176 offset:16384
	ds_read_b128 v[162:165], v176 offset:17408
	ds_read_b128 v[178:181], v176 offset:18432
	ds_read_b128 v[182:185], v176 offset:19456
	ds_read_b128 v[196:199], v176 offset:20480
	ds_read_b128 v[200:203], v176 offset:21504
	ds_read_b128 v[204:207], v176 offset:22528
	ds_read_b128 v[208:211], v176 offset:23552
	global_load_lds_dwordx4 v152, s[4:5]
	s_mov_b32 m0, s23
	s_nop 0
	s_add_u32 vcc_lo, s4, s86
	s_addc_u32 vcc_hi, s5, s87
	global_load_lds_dwordx4 v152, vcc
	s_barrier
	s_waitcnt lgkmcnt(0)
	v_mfma_f32_16x16x32_bf16 v[68:71], v[136:139], v[158:161], v[68:71]
	v_mfma_f32_16x16x32_bf16 v[64:67], v[144:147], v[158:161], v[64:67]
	v_mfma_f32_16x16x32_bf16 v[60:63], v[136:139], v[178:181], v[60:63]
	v_mfma_f32_16x16x32_bf16 v[56:59], v[144:147], v[178:181], v[56:59]
	v_mfma_f32_16x16x32_bf16 v[52:55], v[136:139], v[196:199], v[52:55]
	v_mfma_f32_16x16x32_bf16 v[48:51], v[144:147], v[196:199], v[48:51]
	v_mfma_f32_16x16x32_bf16 v[44:47], v[136:139], v[204:207], v[44:47]
	v_mfma_f32_16x16x32_bf16 v[40:43], v[144:147], v[204:207], v[40:43]
	v_mfma_f32_16x16x32_bf16 v[68:71], v[140:143], v[162:165], v[68:71]
	v_mfma_f32_16x16x32_bf16 v[64:67], v[148:151], v[162:165], v[64:67]
	v_mfma_f32_16x16x32_bf16 v[60:63], v[140:143], v[182:185], v[60:63]
	v_mfma_f32_16x16x32_bf16 v[56:59], v[148:151], v[182:185], v[56:59]
	v_mfma_f32_16x16x32_bf16 v[52:55], v[140:143], v[200:203], v[52:55]
	v_mfma_f32_16x16x32_bf16 v[48:51], v[148:151], v[200:203], v[48:51]
	v_mfma_f32_16x16x32_bf16 v[44:47], v[140:143], v[208:211], v[44:47]
	v_mfma_f32_16x16x32_bf16 v[40:43], v[148:151], v[208:211], v[40:43]
	s_barrier
	s_add_i32 s4, s43, s21
	v_lshl_add_u64 v[136:137], v[2:3], 0, s[0:1]
	s_mov_b32 m0, s4
	s_nop 0
	global_load_lds_dwordx4 v[136:137], off
	v_lshl_add_u64 v[136:137], v[2:3], 0, s[52:53]
	s_add_i32 m0, s4, 0x2000
	s_nop 0
	global_load_lds_dwordx4 v[136:137], off
	s_waitcnt vmcnt(6)
	s_barrier
	v_mfma_f32_16x16x32_bf16 v[36:39], v[212:215], v[158:161], v[36:39]
	v_mfma_f32_16x16x32_bf16 v[32:35], v[220:223], v[158:161], v[32:35]
	v_mfma_f32_16x16x32_bf16 v[28:31], v[212:215], v[178:181], v[28:31]
	v_mfma_f32_16x16x32_bf16 v[24:27], v[220:223], v[178:181], v[24:27]
	v_mfma_f32_16x16x32_bf16 v[20:23], v[212:215], v[196:199], v[20:23]
	v_mfma_f32_16x16x32_bf16 v[16:19], v[220:223], v[196:199], v[16:19]
	v_mfma_f32_16x16x32_bf16 v[12:15], v[212:215], v[204:207], v[12:15]
	v_mfma_f32_16x16x32_bf16 v[8:11], v[220:223], v[204:207], v[8:11]
	v_mfma_f32_16x16x32_bf16 v[36:39], v[216:219], v[162:165], v[36:39]
	v_mfma_f32_16x16x32_bf16 v[32:35], v[224:227], v[162:165], v[32:35]
	v_mfma_f32_16x16x32_bf16 v[28:31], v[216:219], v[182:185], v[28:31]
	v_mfma_f32_16x16x32_bf16 v[24:27], v[224:227], v[182:185], v[24:27]
	v_mfma_f32_16x16x32_bf16 v[20:23], v[216:219], v[200:203], v[20:23]
	v_mfma_f32_16x16x32_bf16 v[16:19], v[224:227], v[200:203], v[16:19]
	v_mfma_f32_16x16x32_bf16 v[12:15], v[216:219], v[208:211], v[12:15]
	v_mfma_f32_16x16x32_bf16 v[8:11], v[224:227], v[208:211], v[8:11]
	s_barrier
; #define G_STAGE(bufoff, gbase, o0, h64) do { \
;         __builtin_amdgcn_global_load_lds((const unsigned*)((const char*)(gbase) + (o0)), (LAS unsigned*)(lds + (bufoff) + ldsw), 16, 0, 0); \
;         __builtin_amdgcn_global_load_lds((const unsigned*)((const char*)(gbase) + (h64) + (o0)), (LAS unsigned*)(lds + (bufoff) + ldsw + 8192), 16, 0, 0); } while (0)
; #define G_LDA(dst, b, h) do { _Pragma("unroll") for (int m = 0; m < 4; ++m) _Pragma("unroll") for (int k = 0; k < 2; ++k) dst[m][k] = *(const LAS bf16x8*)(lds + G_SA(b, h) + aoff + m * 2048 + k * 1024); } while (0)
; #define G_LDB(dst, b, h) do { _Pragma("unroll") for (int n = 0; n < 2; ++n) _Pragma("unroll") for (int k = 0; k < 2; ++k) dst[n][k] = *(const LAS bf16x8*)(lds + G_SB(b, h) + boff + n * 2048 + k * 1024); } while (0)
; #define G_WAIT_L(n) asm volatile("s_waitcnt lgkmcnt(" #n ")" ::: "memory")
; #define G_BAR __builtin_amdgcn_s_barrier()
; #define G_SCHED __builtin_amdgcn_sched_barrier(0)
;     ...
;             G_LDB(B0, 1, 0); G_SCHED; G_LDA(At, 1, 0); G_STAGE(G_SA(0, 1), a2 + chA, cA0, qA);
;             G_WAIT_L(8); G_BAR; G_WAIT_L(0); G_MMA(0, 0, At, B0); G_BAR; G_SCHED;
;             G_LDB(B1, 1, 1); G_STAGE(G_SB(1, 0), b3, cB0, qB);
;             G_BAR; G_WAIT_L(0); G_MMA(0, 1, At, B1); G_BAR;
	s_add_i32 s4, 0, 0x18000
	ds_read_b128 v[136:139], v239 offset:32768
	ds_read_b128 v[140:143], v239 offset:33792
	ds_read_b128 v[144:147], v239 offset:34816
	ds_read_b128 v[148:151], v239 offset:35840
	s_mov_b32 m0, s24
	v_lshl_add_u64 v[172:173], v[166:167], 0, s[88:89]
	ds_read_b128 v[158:161], v176 offset:32768
	ds_read_b128 v[162:165], v176 offset:33792
	ds_read_b128 v[178:181], v176 offset:34816
	ds_read_b128 v[182:185], v176 offset:35840
	ds_read_b128 v[196:199], v176 offset:36864
	ds_read_b128 v[200:203], v176 offset:37888
	ds_read_b128 v[204:207], v176 offset:38912
	ds_read_b128 v[208:211], v176 offset:39936
	global_load_lds_dwordx4 v[172:173], off
	v_lshl_add_u64 v[172:173], v[166:167], 0, s[64:65]
	s_mov_b32 m0, s25
	s_nop 0
	global_load_lds_dwordx4 v[172:173], off
	s_waitcnt lgkmcnt(8)
	s_barrier
	s_waitcnt lgkmcnt(0)
	v_mfma_f32_16x16x32_bf16 v[104:107], v[136:139], v[158:161], v[104:107]
	v_mfma_f32_16x16x32_bf16 v[108:111], v[144:147], v[158:161], v[108:111]
	v_mfma_f32_16x16x32_bf16 v[132:135], v[136:139], v[178:181], v[132:135]
	v_mfma_f32_16x16x32_bf16 v[128:131], v[144:147], v[178:181], v[128:131]
	v_mfma_f32_16x16x32_bf16 v[124:127], v[136:139], v[196:199], v[124:127]
	v_mfma_f32_16x16x32_bf16 v[120:123], v[144:147], v[196:199], v[120:123]
	v_mfma_f32_16x16x32_bf16 v[116:119], v[136:139], v[204:207], v[116:119]
	v_mfma_f32_16x16x32_bf16 v[112:115], v[144:147], v[204:207], v[112:115]
	v_mfma_f32_16x16x32_bf16 v[104:107], v[140:143], v[162:165], v[104:107]
	v_mfma_f32_16x16x32_bf16 v[108:111], v[148:151], v[162:165], v[108:111]
	v_mfma_f32_16x16x32_bf16 v[132:135], v[140:143], v[182:185], v[132:135]
	v_mfma_f32_16x16x32_bf16 v[128:131], v[148:151], v[182:185], v[128:131]
	v_mfma_f32_16x16x32_bf16 v[124:127], v[140:143], v[200:203], v[124:127]
	v_mfma_f32_16x16x32_bf16 v[120:123], v[148:151], v[200:203], v[120:123]
	v_mfma_f32_16x16x32_bf16 v[116:119], v[140:143], v[208:211], v[116:119]
	v_mfma_f32_16x16x32_bf16 v[112:115], v[148:151], v[208:211], v[112:115]
	s_barrier
	s_add_i32 s5, 0, 0x1c000
	s_add_i32 s4, s4, s21
	v_lshl_add_u64 v[172:173], v[2:3], 0, s[46:47]
	s_mov_b32 m0, s4
	ds_read_b128 v[212:215], v239 offset:49152
	ds_read_b128 v[216:219], v239 offset:50176
	ds_read_b128 v[220:223], v239 offset:51200
	ds_read_b128 v[224:227], v239 offset:52224
	global_load_lds_dwordx4 v[172:173], off
	v_lshl_add_u64 v[172:173], v[2:3], 0, s[54:55]
	s_add_i32 m0, s4, 0x2000
	s_nop 0
	global_load_lds_dwordx4 v[172:173], off
	s_barrier
	s_waitcnt lgkmcnt(0)
	v_mfma_f32_16x16x32_bf16 v[100:103], v[212:215], v[158:161], v[100:103]
	v_mfma_f32_16x16x32_bf16 v[96:99], v[220:223], v[158:161], v[96:99]
	v_mfma_f32_16x16x32_bf16 v[92:95], v[212:215], v[178:181], v[92:95]
	v_mfma_f32_16x16x32_bf16 v[88:91], v[220:223], v[178:181], v[88:91]
	v_mfma_f32_16x16x32_bf16 v[84:87], v[212:215], v[196:199], v[84:87]
	v_mfma_f32_16x16x32_bf16 v[80:83], v[220:223], v[196:199], v[80:83]
	v_mfma_f32_16x16x32_bf16 v[76:79], v[212:215], v[204:207], v[76:79]
	v_mfma_f32_16x16x32_bf16 v[72:75], v[220:223], v[204:207], v[72:75]
	v_mfma_f32_16x16x32_bf16 v[100:103], v[216:219], v[162:165], v[100:103]
	v_mfma_f32_16x16x32_bf16 v[96:99], v[224:227], v[162:165], v[96:99]
	v_mfma_f32_16x16x32_bf16 v[92:95], v[216:219], v[182:185], v[92:95]
	v_mfma_f32_16x16x32_bf16 v[88:91], v[224:227], v[182:185], v[88:91]
	v_mfma_f32_16x16x32_bf16 v[84:87], v[216:219], v[200:203], v[84:87]
	v_mfma_f32_16x16x32_bf16 v[80:83], v[224:227], v[200:203], v[80:83]
	v_mfma_f32_16x16x32_bf16 v[76:79], v[216:219], v[208:211], v[76:79]
	v_mfma_f32_16x16x32_bf16 v[72:75], v[224:227], v[208:211], v[72:75]
	s_barrier
; #define G_STAGE(bufoff, gbase, o0, h64) do { \
;         __builtin_amdgcn_global_load_lds((const unsigned*)((const char*)(gbase) + (o0)), (LAS unsigned*)(lds + (bufoff) + ldsw), 16, 0, 0); \
;         __builtin_amdgcn_global_load_lds((const unsigned*)((const char*)(gbase) + (h64) + (o0)), (LAS unsigned*)(lds + (bufoff) + ldsw + 8192), 16, 0, 0); } while (0)
; #define G_LDA(dst, b, h) do { _Pragma("unroll") for (int m = 0; m < 4; ++m) _Pragma("unroll") for (int k = 0; k < 2; ++k) dst[m][k] = *(const LAS bf16x8*)(lds + G_SA(b, h) + aoff + m * 2048 + k * 1024); } while (0)
; #define G_WAIT_V(n) asm volatile("s_waitcnt vmcnt(" #n ")" ::: "memory")
; #define G_WAIT_L(n) asm volatile("s_waitcnt lgkmcnt(" #n ")" ::: "memory")
; #define G_BAR __builtin_amdgcn_s_barrier()
; #define G_SCHED __builtin_amdgcn_sched_barrier(0)
;     ...
;             G_LDA(At, 1, 1); G_STAGE(G_SA(1, 0), a3, cA0, qA);
;             G_BAR; G_WAIT_L(0); G_MMA(1, 0, At, B0); G_BAR; G_SCHED;
;             G_STAGE(G_SB(1, 1), b3 + chB, cB0, qB);
;             G_WAIT_V(6); G_BAR; G_MMA(1, 1, At, B1); G_BAR;
;         }
	s_mov_b32 m0, s26
	v_lshl_add_u64 v[172:173], v[166:167], 0, s[46:47]
	ds_read_b128 v[158:161], v176 offset:49152
	ds_read_b128 v[162:165], v176 offset:50176
	ds_read_b128 v[178:181], v176 offset:51200
	ds_read_b128 v[182:185], v176 offset:52224
	ds_read_b128 v[196:199], v176 offset:53248
	ds_read_b128 v[200:203], v176 offset:54272
	ds_read_b128 v[204:207], v176 offset:55296
	ds_read_b128 v[208:211], v176 offset:56320
	global_load_lds_dwordx4 v[172:173], off
	v_lshl_add_u64 v[166:167], v[166:167], 0, s[66:67]
	s_mov_b32 m0, s27
	s_nop 0
	global_load_lds_dwordx4 v[166:167], off
	s_barrier
	s_waitcnt lgkmcnt(0)
	v_mfma_f32_16x16x32_bf16 v[68:71], v[136:139], v[158:161], v[68:71]
	v_mfma_f32_16x16x32_bf16 v[64:67], v[144:147], v[158:161], v[64:67]
	v_mfma_f32_16x16x32_bf16 v[60:63], v[136:139], v[178:181], v[60:63]
	v_mfma_f32_16x16x32_bf16 v[56:59], v[144:147], v[178:181], v[56:59]
	v_mfma_f32_16x16x32_bf16 v[52:55], v[136:139], v[196:199], v[52:55]
	v_mfma_f32_16x16x32_bf16 v[48:51], v[144:147], v[196:199], v[48:51]
	v_mfma_f32_16x16x32_bf16 v[44:47], v[136:139], v[204:207], v[44:47]
	v_mfma_f32_16x16x32_bf16 v[40:43], v[144:147], v[204:207], v[40:43]
	v_mfma_f32_16x16x32_bf16 v[68:71], v[140:143], v[162:165], v[68:71]
	v_mfma_f32_16x16x32_bf16 v[64:67], v[148:151], v[162:165], v[64:67]
	v_mfma_f32_16x16x32_bf16 v[60:63], v[140:143], v[182:185], v[60:63]
	v_mfma_f32_16x16x32_bf16 v[56:59], v[148:151], v[182:185], v[56:59]
	v_mfma_f32_16x16x32_bf16 v[52:55], v[140:143], v[200:203], v[52:55]
	v_mfma_f32_16x16x32_bf16 v[48:51], v[148:151], v[200:203], v[48:51]
	v_mfma_f32_16x16x32_bf16 v[44:47], v[140:143], v[208:211], v[44:47]
	v_mfma_f32_16x16x32_bf16 v[40:43], v[148:151], v[208:211], v[40:43]
	s_barrier
	s_add_i32 s4, s5, s21
	v_lshl_add_u64 v[136:137], v[2:3], 0, s[50:51]
	s_mov_b32 m0, s4
	v_lshl_add_u64 v[2:3], v[2:3], 0, s[58:59]
	global_load_lds_dwordx4 v[136:137], off
	s_add_i32 m0, s4, 0x2000
	s_nop 0
	global_load_lds_dwordx4 v[2:3], off
	s_add_i32 s18, s18, 2
	s_add_u32 s6, s6, 0x100
	s_addc_u32 s7, s7, 0
	s_add_u32 s8, s8, 0x100
	s_addc_u32 s9, s9, 0
	s_cmp_gt_u32 s18, 5
	s_waitcnt vmcnt(6)
	s_barrier
	v_mfma_f32_16x16x32_bf16 v[36:39], v[212:215], v[158:161], v[36:39]
	v_mfma_f32_16x16x32_bf16 v[32:35], v[220:223], v[158:161], v[32:35]
	v_mfma_f32_16x16x32_bf16 v[28:31], v[212:215], v[178:181], v[28:31]
	v_mfma_f32_16x16x32_bf16 v[24:27], v[220:223], v[178:181], v[24:27]
	v_mfma_f32_16x16x32_bf16 v[20:23], v[212:215], v[196:199], v[20:23]
	v_mfma_f32_16x16x32_bf16 v[16:19], v[220:223], v[196:199], v[16:19]
	v_mfma_f32_16x16x32_bf16 v[12:15], v[212:215], v[204:207], v[12:15]
	v_mfma_f32_16x16x32_bf16 v[8:11], v[220:223], v[204:207], v[8:11]
	v_mfma_f32_16x16x32_bf16 v[36:39], v[216:219], v[162:165], v[36:39]
	v_mfma_f32_16x16x32_bf16 v[32:35], v[224:227], v[162:165], v[32:35]
	v_mfma_f32_16x16x32_bf16 v[28:31], v[216:219], v[182:185], v[28:31]
	v_mfma_f32_16x16x32_bf16 v[24:27], v[224:227], v[182:185], v[24:27]
	v_mfma_f32_16x16x32_bf16 v[20:23], v[216:219], v[200:203], v[20:23]
	v_mfma_f32_16x16x32_bf16 v[16:19], v[224:227], v[200:203], v[16:19]
	v_mfma_f32_16x16x32_bf16 v[12:15], v[216:219], v[208:211], v[12:15]
	v_mfma_f32_16x16x32_bf16 v[8:11], v[224:227], v[208:211], v[8:11]
	s_cbranch_scc0 .Ldb_MG1_cont
	v_readfirstlane_b32 s101, v186
	s_cmpk_gt_u32 s101, 0xff
	s_cbranch_scc1 .Ldb_MG1_young
	s_barrier
	s_mov_b32 s101, 1
	s_setprio 0
	s_branch .Ldb_MG1_exit

; #define G_STAGE(bufoff, gbase, o0, h64) do { \
;         __builtin_amdgcn_global_load_lds((const unsigned*)((const char*)(gbase) + (o0)), (LAS unsigned*)(lds + (bufoff) + ldsw), 16, 0, 0); \
;         __builtin_amdgcn_global_load_lds((const unsigned*)((const char*)(gbase) + (h64) + (o0)), (LAS unsigned*)(lds + (bufoff) + ldsw + 8192), 16, 0, 0); } while (0)
; #define G_LDA(dst, b, h) do { _Pragma("unroll") for (int m = 0; m < 4; ++m) _Pragma("unroll") for (int k = 0; k < 2; ++k) dst[m][k] = *(const LAS bf16x8*)(lds + G_SA(b, h) + aoff + m * 2048 + k * 1024); } while (0)
; #define G_LDB(dst, b, h) do { _Pragma("unroll") for (int n = 0; n < 2; ++n) _Pragma("unroll") for (int k = 0; k < 2; ++k) dst[n][k] = *(const LAS bf16x8*)(lds + G_SB(b, h) + boff + n * 2048 + k * 1024); } while (0)
; #define G_WAIT_L(n) asm volatile("s_waitcnt lgkmcnt(" #n ")" ::: "memory")
; #define G_BAR __builtin_amdgcn_s_barrier()
; #define G_SCHED __builtin_amdgcn_sched_barrier(0)
;     ...
;     for (;;) {
;         const bool has_next = sched_next<PH, SUB>(E.ws, E.layer, ui + 1, nxt, E.x);
;         if (!has_next) nxt = cur;
;         const char* nA = nxt.A; const char* nB = nxt.B;
; #pragma unroll 1
;         for (int t = 0; t < nt; t += 2) {
;             const bool last = (t == nt - 2);
;             const char* a1 = cA + (size_t)(t + 1) * ckA;
;             const char* a2 = last ? nA : cA + (size_t)(t + 2) * ckA; const char* b2 = last ? nB : cB + (size_t)(t + 2) * kB;
;             const char* a3 = a2 + ckA; const char* b3 = b2 + kB;
;             G_LDB(B0, 0, 0); G_SCHED; G_LDA(At, 0, 0); G_STAGE(G_SA(1, 1), a1 + chA, cA0, qA);
;             G_WAIT_L(8); G_BAR; G_WAIT_L(0); G_MMA(0, 0, At, B0); G_BAR; G_SCHED;
.LBB0_1036:
	s_add_u32 s2, s2, 0x40080
	s_addc_u32 s3, s3, 0
	s_add_u32 s6, s6, 0x100
	s_waitcnt lgkmcnt(0)
	s_addc_u32 s7, s7, 0
	s_mov_b32 s15, -2
	s_mov_b64 s[42:43], 0x40000
	s_mov_b64 s[50:51], 0x60000
	s_mov_b64 s[52:53], 0x20080
	s_mov_b64 s[54:55], 0x40080
	s_mov_b64 s[58:59], 0x60080
	s_cmp_eq_u32 s101, 2
	s_cselect_b32 s101, 0, s101
	s_setprio 1
	v_add_u32_e32 v255, 0x10000, v181
	s_add_u32 s4, s2, 0xfffc0080
	s_addc_u32 s5, s3, -1
	s_add_i32 s33, 0, 0x10000
	ds_read_b128 v[136:139], v255 offset:0
	ds_read_b128 v[140:143], v255 offset:1024
	ds_read_b128 v[144:147], v255 offset:2048
	ds_read_b128 v[148:151], v255 offset:3072
	s_cmp_eq_u32 s15, 12
	s_cselect_b32 s5, s17, s5
	s_cselect_b32 s4, s16, s4
	s_cselect_b32 s21, s19, s7
	s_cselect_b32 s20, s18, s6
	s_add_i32 m0, s24, 0xc000
	ds_read_b128 v[152:155], v182
	ds_read_b128 v[156:159], v182 offset:1024
	ds_read_b128 v[160:163], v182 offset:2048
	ds_read_b128 v[172:175], v182 offset:3072
	ds_read_b128 v[176:179], v182 offset:4096
	ds_read_b128 v[196:199], v182 offset:5120
	ds_read_b128 v[200:203], v182 offset:6144
	ds_read_b128 v[204:207], v182 offset:7168
	global_load_lds_dwordx4 v166, s[2:3]
	s_add_i32 m0, s24, 0xe000
	s_nop 0
	s_add_u32 vcc_lo, s2, s0
	s_addc_u32 vcc_hi, s3, s1
	global_load_lds_dwordx4 v166, vcc
	s_waitcnt lgkmcnt(8)
	s_cmp_eq_u32 s101, 1
	s_cbranch_scc1 .Ldb_WOUT_skp
	s_barrier

; #define G_STAGE(bufoff, gbase, o0, h64) do { \
;         __builtin_amdgcn_global_load_lds((const unsigned*)((const char*)(gbase) + (o0)), (LAS unsigned*)(lds + (bufoff) + ldsw), 16, 0, 0); \
;         __builtin_amdgcn_global_load_lds((const unsigned*)((const char*)(gbase) + (h64) + (o0)), (LAS unsigned*)(lds + (bufoff) + ldsw + 8192), 16, 0, 0); } while (0)
; #define G_LDA(dst, b, h) do { _Pragma("unroll") for (int m = 0; m < 4; ++m) _Pragma("unroll") for (int k = 0; k < 2; ++k) dst[m][k] = *(const LAS bf16x8*)(lds + G_SA(b, h) + aoff + m * 2048 + k * 1024); } while (0)
; #define G_LDB(dst, b, h) do { _Pragma("unroll") for (int n = 0; n < 2; ++n) _Pragma("unroll") for (int k = 0; k < 2; ++k) dst[n][k] = *(const LAS bf16x8*)(lds + G_SB(b, h) + boff + n * 2048 + k * 1024); } while (0)
; #define G_WAIT_L(n) asm volatile("s_waitcnt lgkmcnt(" #n ")" ::: "memory")
; #define G_BAR __builtin_amdgcn_s_barrier()
; #define G_SCHED __builtin_amdgcn_sched_barrier(0)
;     ...
;     for (;;) {
;         const bool has_next = sched_next<PH, SUB>(E.ws, E.layer, ui + 1, nxt, E.x);
;         if (!has_next) nxt = cur;
;         const char* nA = nxt.A; const char* nB = nxt.B;
; #pragma unroll 1
;         for (int t = 0; t < nt; t += 2) {
;             const bool last = (t == nt - 2);
;             const char* a1 = cA + (size_t)(t + 1) * ckA;
;             const char* a2 = last ? nA : cA + (size_t)(t + 2) * ckA; const char* b2 = last ? nB : cB + (size_t)(t + 2) * kB;
;             const char* a3 = a2 + ckA; const char* b3 = b2 + kB;
;             G_LDB(B0, 0, 0); G_SCHED; G_LDA(At, 0, 0); G_STAGE(G_SA(1, 1), a1 + chA, cA0, qA);
;             G_WAIT_L(8); G_BAR; G_WAIT_L(0); G_MMA(0, 0, At, B0); G_BAR; G_SCHED;
.LBB0_1119:
	s_add_u32 s2, s16, 0x40080
	s_addc_u32 s3, s17, 0
	s_add_u32 s16, s18, 0x100
	s_addc_u32 s17, s19, 0
	s_mov_b32 s18, -2
	s_mov_b64 s[42:43], 0x40000
	s_mov_b64 s[50:51], 0x60000
	s_mov_b64 s[52:53], 0x20080
	s_mov_b64 s[54:55], 0x40080
	s_mov_b64 s[58:59], 0x60080
	s_cmp_eq_u32 s101, 2
	s_cselect_b32 s101, 0, s101
	s_setprio 1
	v_add_u32_e32 v235, 0x10000, v149
	s_add_u32 s4, s2, 0xfffc0080
	s_addc_u32 s5, s3, -1
	s_add_i32 s19, 0, 0x10000
	ds_read_b128 v[140:143], v235 offset:0
	ds_read_b128 v[144:147], v235 offset:1024
	ds_read_b128 v[152:155], v235 offset:2048
	ds_read_b128 v[156:159], v235 offset:3072
	s_cmp_eq_u32 s18, 12
	s_cselect_b32 s5, s13, s5
	s_cselect_b32 s4, s12, s4
	s_cselect_b32 s41, s15, s17
	s_cselect_b32 s40, s14, s16
	s_add_i32 m0, s26, 0xc000
	ds_read_b128 v[160:163], v150
	ds_read_b128 v[164:167], v150 offset:1024
	ds_read_b128 v[172:175], v150 offset:2048
	ds_read_b128 v[176:179], v150 offset:3072
	ds_read_b128 v[180:183], v150 offset:4096
	ds_read_b128 v[196:199], v150 offset:5120
	ds_read_b128 v[200:203], v150 offset:6144
	ds_read_b128 v[204:207], v150 offset:7168
	global_load_lds_dwordx4 v138, s[2:3]
	s_add_i32 m0, s26, 0xe000
	s_nop 0
	s_add_u32 vcc_lo, s2, s0
	s_addc_u32 vcc_hi, s3, s1
	global_load_lds_dwordx4 v138, vcc
	s_waitcnt lgkmcnt(8)
	s_cmp_eq_u32 s101, 1
	s_cbranch_scc1 .Ldb_FFI_skp
	s_barrier

; #define G_STAGE(bufoff, gbase, o0, h64) do { \
;         __builtin_amdgcn_global_load_lds((const unsigned*)((const char*)(gbase) + (o0)), (LAS unsigned*)(lds + (bufoff) + ldsw), 16, 0, 0); \
;         __builtin_amdgcn_global_load_lds((const unsigned*)((const char*)(gbase) + (h64) + (o0)), (LAS unsigned*)(lds + (bufoff) + ldsw + 8192), 16, 0, 0); } while (0)
; #define G_LDA(dst, b, h) do { _Pragma("unroll") for (int m = 0; m < 4; ++m) _Pragma("unroll") for (int k = 0; k < 2; ++k) dst[m][k] = *(const LAS bf16x8*)(lds + G_SA(b, h) + aoff + m * 2048 + k * 1024); } while (0)
; #define G_LDB(dst, b, h) do { _Pragma("unroll") for (int n = 0; n < 2; ++n) _Pragma("unroll") for (int k = 0; k < 2; ++k) dst[n][k] = *(const LAS bf16x8*)(lds + G_SB(b, h) + boff + n * 2048 + k * 1024); } while (0)
; #define G_WAIT_L(n) asm volatile("s_waitcnt lgkmcnt(" #n ")" ::: "memory")
; #define G_BAR __builtin_amdgcn_s_barrier()
; #define G_SCHED __builtin_amdgcn_sched_barrier(0)
;     ...
;     for (;;) {
;         const bool has_next = sched_next<PH, SUB>(E.ws, E.layer, ui + 1, nxt, E.x);
;         if (!has_next) nxt = cur;
;         const char* nA = nxt.A; const char* nB = nxt.B;
; #pragma unroll 1
;         for (int t = 0; t < nt; t += 2) {
;             const bool last = (t == nt - 2);
;             const char* a1 = cA + (size_t)(t + 1) * ckA;
;             const char* a2 = last ? nA : cA + (size_t)(t + 2) * ckA; const char* b2 = last ? nB : cB + (size_t)(t + 2) * kB;
;             const char* a3 = a2 + ckA; const char* b3 = b2 + kB;
;             G_LDB(B0, 0, 0); G_SCHED; G_LDA(At, 0, 0); G_STAGE(G_SA(1, 1), a1 + chA, cA0, qA);
;             G_WAIT_L(8); G_BAR; G_WAIT_L(0); G_MMA(0, 0, At, B0); G_BAR; G_SCHED;
.LBB0_1184:
	s_add_u32 s2, s2, 0xb0080
	s_addc_u32 s3, s3, 0
	s_add_u32 s6, s6, 0x100
	s_waitcnt lgkmcnt(0)
	s_addc_u32 s7, s7, 0
	s_mov_b32 s21, -2
	s_mov_b64 s[52:53], 0xb0080
	s_mov_b64 s[54:55], 0x108080
	s_cmp_eq_u32 s101, 2
	s_cselect_b32 s101, 0, s101
	s_setprio 1
	v_add_u32_e32 v255, 0x10000, v185
	s_add_u32 s4, s2, 0xfff50080
	s_addc_u32 s5, s3, -1
	s_add_i32 s33, 0, 0x10000
	ds_read_b128 v[136:139], v255 offset:0
	ds_read_b128 v[140:143], v255 offset:1024
	ds_read_b128 v[144:147], v255 offset:2048
	ds_read_b128 v[148:151], v255 offset:3072
	s_cmp_eq_u32 s21, 40
	s_cselect_b32 s5, s17, s5
	s_cselect_b32 s4, s16, s4
	s_cselect_b32 s23, s19, s7
	s_cselect_b32 s22, s18, s6
	s_add_i32 m0, s26, 0xc000
	ds_read_b128 v[152:155], v195
	ds_read_b128 v[156:159], v195 offset:1024
	ds_read_b128 v[160:163], v195 offset:2048
	ds_read_b128 v[164:167], v195 offset:3072
	ds_read_b128 v[176:179], v195 offset:4096
	ds_read_b128 v[180:183], v195 offset:5120
	ds_read_b128 v[196:199], v195 offset:6144
	ds_read_b128 v[200:203], v195 offset:7168
	global_load_lds_dwordx4 v174, s[2:3]
	s_add_i32 m0, s26, 0xe000
	s_nop 0
	s_add_u32 vcc_lo, s2, s86
	s_addc_u32 vcc_hi, s3, s87
	global_load_lds_dwordx4 v174, vcc
	s_waitcnt lgkmcnt(8)
	s_cmp_eq_u32 s101, 1
	s_cbranch_scc1 .Ldb_FFO_skp
	s_barrier

; #define G_STAGE(bufoff, gbase, o0, h64) do { \
;         __builtin_amdgcn_global_load_lds((const unsigned*)((const char*)(gbase) + (o0)), (LAS unsigned*)(lds + (bufoff) + ldsw), 16, 0, 0); \
;         __builtin_amdgcn_global_load_lds((const unsigned*)((const char*)(gbase) + (h64) + (o0)), (LAS unsigned*)(lds + (bufoff) + ldsw + 8192), 16, 0, 0); } while (0)
; #define G_LDA(dst, b, h) do { _Pragma("unroll") for (int m = 0; m < 4; ++m) _Pragma("unroll") for (int k = 0; k < 2; ++k) dst[m][k] = *(const LAS bf16x8*)(lds + G_SA(b, h) + aoff + m * 2048 + k * 1024); } while (0)
; #define G_LDB(dst, b, h) do { _Pragma("unroll") for (int n = 0; n < 2; ++n) _Pragma("unroll") for (int k = 0; k < 2; ++k) dst[n][k] = *(const LAS bf16x8*)(lds + G_SB(b, h) + boff + n * 2048 + k * 1024); } while (0)
; #define G_WAIT_L(n) asm volatile("s_waitcnt lgkmcnt(" #n ")" ::: "memory")
; #define G_BAR __builtin_amdgcn_s_barrier()
; #define G_SCHED __builtin_amdgcn_sched_barrier(0)
;     ...
;     for (;;) {
;         const bool has_next = sched_next<PH, SUB>(E.ws, E.layer, ui + 1, nxt, E.x);
;         if (!has_next) nxt = cur;
;         const char* nA = nxt.A; const char* nB = nxt.B;
; #pragma unroll 1
;         for (int t = 0; t < nt; t += 2) {
;             const bool last = (t == nt - 2);
;             const char* a1 = cA + (size_t)(t + 1) * ckA;
;             const char* a2 = last ? nA : cA + (size_t)(t + 2) * ckA; const char* b2 = last ? nB : cB + (size_t)(t + 2) * kB;
;             const char* a3 = a2 + ckA; const char* b3 = b2 + kB;
;             G_LDB(B0, 0, 0); G_SCHED; G_LDA(At, 0, 0); G_STAGE(G_SA(1, 1), a1 + chA, cA0, qA);
;             G_WAIT_L(8); G_BAR; G_WAIT_L(0); G_MMA(0, 0, At, B0); G_BAR; G_SCHED;
.LBB0_1259:
	s_mov_b64 s[18:19], 0
	s_mov_b64 s[14:15], -1
	s_mov_b64 s[16:17], 0
	s_mov_b64 s[58:59], 0x10000
	s_cmp_eq_u32 s101, 2
	s_cselect_b32 s101, 0, s101
	s_setprio 1
	v_add_u32_e32 v255, 0x10000, v137
	s_add_u32 s22, s10, s18
	s_addc_u32 s23, s11, s19
	s_add_u32 s20, s22, 0x100
	s_addc_u32 s21, s23, 0
	s_and_b64 s[4:5], s[16:17], exec
	s_cselect_b32 s20, s6, s20
	s_cselect_b32 s21, s7, s21
	s_add_u32 s4, s12, s18
	s_addc_u32 s5, s13, s19
	s_add_u32 s18, s4, 0x100
	s_addc_u32 s19, s5, 0
	s_add_i32 s44, 0, 0x10000
	ds_read_b128 v[140:143], v255 offset:0
	ds_read_b128 v[144:147], v255 offset:1024
	ds_read_b128 v[148:151], v255 offset:2048
	ds_read_b128 v[152:155], v255 offset:3072
	s_and_b64 s[4:5], s[16:17], exec
	s_cselect_b32 s16, s8, s18
	s_cselect_b32 s17, s9, s19
	s_add_i32 s5, 0, 0x14000
	s_add_i32 s43, 0, 0x18000
	s_add_i32 s18, 0, 0x1c000
	s_add_i32 s45, s44, s25
	s_add_i32 s51, s5, s25
	s_add_i32 s19, s43, s25
	s_add_i32 s53, s18, s25
	s_mov_b64 s[64:65], 0x8000
	s_mov_b64 s[62:63], 0x10080
	s_add_i32 m0, s31, 0xc000
	s_add_i32 s4, s31, 0xe000
	s_add_i32 s54, s45, 0x2000
	s_add_i32 s50, s51, 0x2000
	s_add_i32 s44, s19, 0x2000
	s_add_i32 s52, s53, 0x2000
	ds_read_b128 v[156:159], v138
	ds_read_b128 v[160:163], v138 offset:1024
	ds_read_b128 v[164:167], v138 offset:2048
	ds_read_b128 v[172:175], v138 offset:3072
	ds_read_b128 v[176:179], v138 offset:4096
	ds_read_b128 v[180:183], v138 offset:5120
	ds_read_b128 v[196:199], v138 offset:6144
	ds_read_b128 v[200:203], v138 offset:7168
	s_add_u32 vcc_lo, s22, s62
	s_addc_u32 vcc_hi, s23, s63
	global_load_lds_dwordx4 v2, vcc
	s_mov_b32 m0, s4
	s_nop 0
	s_add_u32 vcc_lo, s22, s68
	s_addc_u32 vcc_hi, s23, s69
	global_load_lds_dwordx4 v2, vcc
	s_waitcnt lgkmcnt(8)
	s_cmp_eq_u32 s101, 1
	s_cbranch_scc1 .Ldb_PLE0_skp
	s_barrier

; #define G_STAGE(bufoff, gbase, o0, h64) do { \
;         __builtin_amdgcn_global_load_lds((const unsigned*)((const char*)(gbase) + (o0)), (LAS unsigned*)(lds + (bufoff) + ldsw), 16, 0, 0); \
;         __builtin_amdgcn_global_load_lds((const unsigned*)((const char*)(gbase) + (h64) + (o0)), (LAS unsigned*)(lds + (bufoff) + ldsw + 8192), 16, 0, 0); } while (0)
; #define G_LDA(dst, b, h) do { _Pragma("unroll") for (int m = 0; m < 4; ++m) _Pragma("unroll") for (int k = 0; k < 2; ++k) dst[m][k] = *(const LAS bf16x8*)(lds + G_SA(b, h) + aoff + m * 2048 + k * 1024); } while (0)
; #define G_LDB(dst, b, h) do { _Pragma("unroll") for (int n = 0; n < 2; ++n) _Pragma("unroll") for (int k = 0; k < 2; ++k) dst[n][k] = *(const LAS bf16x8*)(lds + G_SB(b, h) + boff + n * 2048 + k * 1024); } while (0)
; #define G_WAIT_L(n) asm volatile("s_waitcnt lgkmcnt(" #n ")" ::: "memory")
; #define G_BAR __builtin_amdgcn_s_barrier()
; #define G_SCHED __builtin_amdgcn_sched_barrier(0)
;     ...
;     for (;;) {
;         const bool has_next = sched_next<PH, SUB>(E.ws, E.layer, ui + 1, nxt, E.x);
;         if (!has_next) nxt = cur;
;         const char* nA = nxt.A; const char* nB = nxt.B;
; #pragma unroll 1
;         for (int t = 0; t < nt; t += 2) {
;             const bool last = (t == nt - 2);
;             const char* a1 = cA + (size_t)(t + 1) * ckA;
;             const char* a2 = last ? nA : cA + (size_t)(t + 2) * ckA; const char* b2 = last ? nB : cB + (size_t)(t + 2) * kB;
;             const char* a3 = a2 + ckA; const char* b3 = b2 + kB;
;             G_LDB(B0, 0, 0); G_SCHED; G_LDA(At, 0, 0); G_STAGE(G_SA(1, 1), a1 + chA, cA0, qA);
;             G_WAIT_L(8); G_BAR; G_WAIT_L(0); G_MMA(0, 0, At, B0); G_BAR; G_SCHED;
.LBB0_1282:
	s_add_u32 s2, s24, 0x40080
	s_addc_u32 s3, s25, 0
	s_add_u32 s22, s22, 0x100
	s_waitcnt lgkmcnt(0)
	s_addc_u32 s23, s23, 0
	s_mov_b32 s24, -2
	s_mov_b64 s[54:55], 0x40000
	s_mov_b64 s[58:59], 0x60000
	s_mov_b64 s[62:63], 0x20080
	s_mov_b64 s[64:65], 0x40080
	s_mov_b64 s[66:67], 0x60080
	s_cmp_eq_u32 s101, 2
	s_cselect_b32 s101, 0, s101
	s_setprio 1
	v_add_u32_e32 v255, 0x10000, v181
	s_add_u32 s4, s2, 0xfffc0080
	s_addc_u32 s5, s3, -1
	s_add_i32 s25, 0, 0x10000
	ds_read_b128 v[136:139], v255 offset:0
	ds_read_b128 v[140:143], v255 offset:1024
	ds_read_b128 v[144:147], v255 offset:2048
	ds_read_b128 v[148:151], v255 offset:3072
	s_cmp_eq_u32 s24, 12
	s_cselect_b32 s5, s19, s5
	s_cselect_b32 s4, s18, s4
	s_cselect_b32 s41, s21, s23
	s_cselect_b32 s40, s20, s22
	s_add_i32 m0, s29, 0xc000
	ds_read_b128 v[152:155], v182
	ds_read_b128 v[160:163], v182 offset:1024
	ds_read_b128 v[164:167], v182 offset:2048
	ds_read_b128 v[172:175], v182 offset:3072
	ds_read_b128 v[176:179], v182 offset:4096
	ds_read_b128 v[196:199], v182 offset:5120
	ds_read_b128 v[200:203], v182 offset:6144
	ds_read_b128 v[204:207], v182 offset:7168
	global_load_lds_dwordx4 v158, s[2:3]
	s_add_i32 m0, s29, 0xe000
	s_nop 0
	s_add_u32 vcc_lo, s2, s0
	s_addc_u32 vcc_hi, s3, s1
	global_load_lds_dwordx4 v158, vcc
	s_waitcnt lgkmcnt(8)
	s_cmp_eq_u32 s101, 1
	s_cbranch_scc1 .Ldb_PLE1_skp
	s_barrier
